# layer-0 phase boundary uses the XCD grid barrier like all other boundaries instead of cooperative-groups grid.sync
# speedup vs baseline: 1.0207x; 1.0114x over previous
; #define GRID_SYNC() do { XcdBarrier xb_; xb_.bar = (unsigned*)launder_ptr(P.ws); xb_.x = xb_xcc_id(); xb_.st = (volatile LAS unsigned*)((LAS unsigned char*)lds_raw + LDS_BYTES - 64); xcd_barrier(xb_); } while (0)
; __device__ __forceinline__ void xcd_barrier(const XcdBarrier& b) {
;     asm volatile("s_waitcnt vmcnt(0)" ::: "memory");
;     __syncthreads();
;     if (threadIdx.x == 0) {
;         unsigned* bar = b.bar;
;         __builtin_amdgcn_s_waitcnt(0);
;         unsigned nloc = b.st[0], nx = b.st[1];
;         if (nloc == 0u) { xcd_barrier_complete(bar, b.x, nloc, nx); b.st[0] = nloc; b.st[1] = nx; }
; __global__ void __launch_bounds__(512, 2) fwd_megakernel(Params P) {
;     ...
;         if (l == 0) grid.sync(); else GRID_SYNC();
.LBB0_96:
	v_readlane_b32 s6, v255, 19
	v_readlane_b32 s7, v255, 20
	s_mov_b64 s[2:3], -1
	s_and_b64 vcc, exec, s[6:7]
	s_mov_b64 s[38:39], s[94:95]
	s_getreg_b32 s5, hwreg(HW_REG_XCC_ID, 0, 4)
	s_waitcnt vmcnt(0)
	s_waitcnt lgkmcnt(0)
	s_barrier
	s_mov_b64 s[2:3], exec
	v_readlane_b32 s6, v254, 61
	v_readlane_b32 s7, v254, 62
	s_and_b64 s[6:7], s[2:3], s[6:7]
	s_mov_b64 exec, s[6:7]
	s_cbranch_execz .LBB0_141
	v_readlane_b32 s6, v255, 3
	s_waitcnt vmcnt(0) expcnt(0) lgkmcnt(0)
	s_and_b32 s5, s5, 15
	v_mov_b32_e32 v1, s6
	ds_read_b32 v4, v1
	v_readlane_b32 s6, v255, 4
	s_waitcnt lgkmcnt(0)
	v_cmp_ne_u32_e32 vcc, 0, v4
	v_mov_b32_e32 v1, s6
	ds_read_b32 v2, v1
	s_cbranch_vccnz .LBB0_112
	s_add_u32 s6, s38, 0x1000
	s_addc_u32 s7, s39, 0
	s_add_u32 s8, s38, 0x1100
	s_addc_u32 s9, s39, 0
	s_add_u32 s10, s38, 0x1200
	s_addc_u32 s11, s39, 0
	s_add_u32 s12, s38, 0x1300
	s_addc_u32 s13, s39, 0
	s_mov_b32 s34, 1
	s_mov_b64 s[14:15], 0
	s_branch .LBB0_102
